# hand-written RWKV-7 recurrence item: packed f32 math, 16-lane prep mapping, no redundant per-rg bonus work
# speedup vs baseline: 1.0697x; 1.0697x over previous
; __device__ __forceinline__ int otid() { int t = threadIdx.x; asm volatile("" : "+v"(t)); return t; }
; __device__ __forceinline__ void rwkv_item(const Params& p, int item, float* sm) {
;     ...
;   bf16_t* yr = yraw_ptr(p, b);
;   constexpr int TC = 16;
;   constexpr int BUF = 5 * TC * 64 + TC * 16 + TC + TC * 16;
;   const int tid = otid(), lane = tid & 63, wave = tid >> 6;
;   const int sub = lane & 15, rowl = wave * 4 + (lane >> 4);
;   const int ltt = tid >> 4, lrr = tid & 15;
;   const int ch = h * 64 + lane;
;   const float kkw = p.k_k[ch], kaw = p.k_a[ch], rkw = p.r_k[ch];
;   const size_t rowb = (size_t)b * LP;
;   float S0 = 0.f, S1 = 0.f, S2 = 0.f, S3 = 0.f;
;   bf16_t pr0, pr1, pr2, pr3, pk0, pk1, pk2, pk3, pa0, pa1, pa2, pa3, pw0, pw1, pw2, pw3, pv;
;     ...
;   __syncthreads();
;   RW_LOAD(PADR)
;   RW_STORE(0, PADR)
;   __syncthreads();
.LBB0_505:
	s_lshr_b32 s2, s13, 2
	s_and_b32 s18, s13, 3
	s_lshr_b32 s19, s2, 4
	s_and_b32 s2, s2, 15
	s_mul_i32 s22, s19, 0x2080
	s_add_i32 s22, s22, 0x70
	v_readlane_b32 s24, v247, 1
	v_readlane_b32 s25, v247, 2
	v_readlane_b32 s26, v247, 3
	v_readlane_b32 s27, v247, 4
	v_and_b32_e32 v137, 15, v2
	v_lshrrev_b32_e32 v138, 4, v2
	s_add_u32 s4, s26, 0xb600000
	s_addc_u32 s5, s27, 0
	s_mov_b32 s6, s24
	s_mov_b32 s7, s25
	s_add_u32 s8, s26, 0x19d90000
	s_addc_u32 s9, s27, 0
	s_add_u32 s14, s26, 0x18d50000
	s_addc_u32 s15, s27, 0
	s_add_u32 s16, s26, 0x19980000
	s_addc_u32 s17, s27, 0
	s_cmp_lt_u32 s19, 2
	s_cbranch_scc1 .Lrw_ylo
	s_add_i32 s23, s19, -2
	s_mul_i32 s23, s23, 0x1040000
	s_add_u32 s10, s24, 0x4100000
	s_addc_u32 s11, s25, 0
	s_branch .Lrw_yjoin
.Lrw_ylo:
	s_mul_i32 s23, s19, 0x1040000
	s_add_u32 s10, s26, 0x1de90000
	s_addc_u32 s11, s27, 0
.Lrw_yjoin:
	s_add_u32 s10, s10, s23
	s_addc_u32 s11, s11, 0
	v_readlane_b32 s24, v247, 9
	v_readlane_b32 s25, v247, 10
	v_readlane_b32 s26, v247, 11
	v_readlane_b32 s27, v247, 12
	s_lshl_b32 s23, s2, 8
	v_lshl_add_u32 v139, v137, 4, s23
	s_nop 1
	global_load_dwordx4 v[16:19], v139, s[24:25]
	global_load_dwordx4 v[20:23], v139, s[26:27]
	v_readlane_b32 s24, v247, 13
	v_readlane_b32 s25, v247, 14
	v_lshlrev_b32_e32 v47, 4, v137
	v_lshlrev_b32_e32 v136, 6, v138
	v_add_u32_e32 v136, 20480, v136
	v_lshlrev_b32_e32 v132, 4, v2
	v_lshl_add_u32 v133, v137, 4, v138
	v_lshlrev_b32_e32 v133, 2, v133
	v_add_u32_e32 v133, 20480, v133
	global_load_dwordx4 v[24:27], v139, s[24:25]
	v_lshlrev_b32_e32 v134, 2, v138
	v_add_u32_e32 v134, 21504, v134
	v_lshlrev_b32_e32 v135, 2, v2
	v_add_u32_e32 v135, 21504, v135
	v_add_u32_e32 v140, s22, v138
	s_lshl_b32 s23, s2, 7
	v_lshl_add_u32 v141, v137, 3, s23
	s_movk_i32 s19, 0x1800
	v_mad_u32_u24 v28, v140, s19, v141
	v_lshl_add_u32 v29, v140, 11, v141
	s_lshl_b32 s19, s18, 5
	s_add_i32 s19, s19, s23
	v_lshl_add_u32 v142, v137, 1, s19
	s_movk_i32 s23, 0x1800
	v_mad_u32_u24 v30, v140, s23, v142
	v_add_u32_e32 v30, 0x1000, v30
	v_add_u32_e32 v143, 0x70, v138
	v_lshl_add_u32 v31, v143, 11, v142
	s_lshl_b32 s19, s2, 4
	s_lshl_b32 s23, s18, 2
	s_add_i32 s19, s19, s23
	v_lshl_add_u32 v32, v140, 8, s19
	s_lshl_b32 s19, s2, 2
	v_lshl_add_u32 v33, v140, 6, s19
	s_mov_b32 s20, -1.0
	s_mov_b32 s21, -1.0
	s_mov_b32 s30, 1.0
	s_mov_b32 s31, 1.0
	s_mov_b32 s22, 0xbfb8aa3b
	s_mov_b32 s23, 0xbfb8aa3b
	v_mov_b32_e32 v12, 0
	v_mov_b32_e32 v13, 0
	v_mov_b32_e32 v14, 0
	v_mov_b32_e32 v15, 0
	s_barrier
	global_load_dwordx2 v[34:35], v28, s[4:5]
	global_load_dwordx2 v[36:37], v28, s[4:5] offset:2048
	global_load_dwordx2 v[38:39], v29, s[6:7]
	global_load_dwordx2 v[40:41], v29, s[8:9]
	global_load_ushort v42, v30, s[4:5]
	v_mov_b32_e32 v43, v132
	v_mov_b32_e32 v44, v133
	s_waitcnt vmcnt(0)
	v_lshlrev_b32_e32 v48, 16, v34
	v_and_b32_e32 v49, 0xffff0000, v34
	v_lshlrev_b32_e32 v50, 16, v35
	v_and_b32_e32 v51, 0xffff0000, v35
	v_lshlrev_b32_e32 v52, 16, v36
	v_and_b32_e32 v53, 0xffff0000, v36
	v_lshlrev_b32_e32 v54, 16, v37
	v_and_b32_e32 v55, 0xffff0000, v37
	v_lshlrev_b32_e32 v56, 16, v38
	v_and_b32_e32 v57, 0xffff0000, v38
	v_lshlrev_b32_e32 v58, 16, v39
	v_and_b32_e32 v59, 0xffff0000, v39
	v_lshlrev_b32_e32 v60, 16, v40
	v_and_b32_e32 v61, 0xffff0000, v40
	v_lshlrev_b32_e32 v62, 16, v41
	v_and_b32_e32 v63, 0xffff0000, v41
	v_lshlrev_b32_e32 v64, 16, v42
	v_pk_mul_f32 v[68:69], v[52:53], v[16:17]
	v_pk_mul_f32 v[70:71], v[54:55], v[18:19]
	v_pk_mul_f32 v[72:73], v[68:69], v[68:69]
	v_pk_fma_f32 v[72:73], v[70:71], v[70:71], v[72:73]
	v_pk_add_f32 v[76:77], v[56:57], s[20:21]
	v_add_f32_e32 v74, v72, v73
	v_pk_add_f32 v[78:79], v[58:59], s[20:21]
	v_pk_mul_f32 v[84:85], v[60:61], s[22:23]
	v_add_f32_dpp v74, v74, v74 quad_perm:[1,0,3,2] row_mask:0xf bank_mask:0xf bound_ctrl:1
	v_pk_mul_f32 v[86:87], v[62:63], s[22:23]
	v_pk_fma_f32 v[76:77], v[76:77], v[20:21], s[30:31]
	v_add_f32_dpp v74, v74, v74 quad_perm:[2,3,0,1] row_mask:0xf bank_mask:0xf bound_ctrl:1
	v_pk_fma_f32 v[78:79], v[78:79], v[22:23], s[30:31]
	v_exp_f32_e32 v84, v84
	v_add_f32_dpp v74, v74, v74 row_half_mirror row_mask:0xf bank_mask:0xf bound_ctrl:1
	v_exp_f32_e32 v85, v85
	v_exp_f32_e32 v86, v86
	v_add_f32_dpp v74, v74, v74 row_mirror row_mask:0xf bank_mask:0xf bound_ctrl:1
	v_exp_f32_e32 v87, v87
	v_pk_mul_f32 v[80:81], v[52:53], v[76:77]
	v_add_f32_e32 v74, 0x358637bd, v74
	v_pk_mul_f32 v[82:83], v[54:55], v[78:79]
	v_rsq_f32_e32 v120, v74
	ds_write_b128 v43, v[84:87]
	ds_write_b128 v43, v[48:51] offset:16384
	ds_write_b32 v44, v64
	ds_write_b128 v43, v[80:83] offset:4096
	v_pk_mul_f32 v[124:125], v[68:69], v[120:121] op_sel_hi:[1,0] neg_lo:[0,1] neg_hi:[0,1]
	v_pk_mul_f32 v[126:127], v[70:71], v[120:121] op_sel_hi:[1,0] neg_lo:[0,1] neg_hi:[0,1]
	v_pk_mul_f32 v[100:101], v[124:125], v[56:57] neg_lo:[1,0] neg_hi:[1,0]
	v_pk_mul_f32 v[102:103], v[126:127], v[58:59] neg_lo:[1,0] neg_hi:[1,0]
	ds_write_b128 v43, v[124:127] offset:8192
	ds_write_b128 v43, v[100:103] offset:12288
	s_cmp_lg_u32 s18, 0
	s_cbranch_scc1 .Lrw_nosb_p0
	v_pk_mul_f32 v[104:105], v[48:49], v[80:81]
	v_pk_mul_f32 v[106:107], v[50:51], v[82:83]
	v_pk_mul_f32 v[108:109], v[104:105], v[24:25]
	v_pk_fma_f32 v[108:109], v[106:107], v[26:27], v[108:109]
	v_add_f32_e32 v110, v108, v109
	s_nop 1
	v_add_f32_dpp v110, v110, v110 quad_perm:[1,0,3,2] row_mask:0xf bank_mask:0xf bound_ctrl:1
	s_nop 1
	v_add_f32_dpp v110, v110, v110 quad_perm:[2,3,0,1] row_mask:0xf bank_mask:0xf bound_ctrl:1
	s_nop 1
	v_add_f32_dpp v110, v110, v110 row_half_mirror row_mask:0xf bank_mask:0xf bound_ctrl:1
	s_nop 1
	v_add_f32_dpp v110, v110, v110 row_mirror row_mask:0xf bank_mask:0xf bound_ctrl:1
	global_store_dword v33, v110, s[16:17]
; __device__ __forceinline__ void rwkv_item(const Params& p, int item, float* sm) {
;     ...
;   constexpr int NCH = (LP - PADR) / TC;
;   for (int c = 0; c < NCH; c++) {
;     const int bi = c & 1;
;     const int t0 = PADR + c * TC;
;     if (c + 1 < NCH) RW_LOAD(t0 + TC)
;     {
;       const float* bw = sm + bi * BUF;
;       const float* bv = bw + 5 * TC * 64;
;       float* by = sm + bi * BUF + 5 * TC * 64 + TC * 16 + TC;
;       float yreg[TC];
; #pragma unroll
;       for (int t = 0; t < TC; t++) {
;         const float4 w4 = *(const float4*)(bw + 0 * TC * 64 + t * 64 + sub * 4);
;         const float4 k4 = *(const float4*)(bw + 1 * TC * 64 + t * 64 + sub * 4);
;         const float4 a4 = *(const float4*)(bw + 2 * TC * 64 + t * 64 + sub * 4);
;         const float4 b4 = *(const float4*)(bw + 3 * TC * 64 + t * 64 + sub * 4);
;         const float4 r4 = *(const float4*)(bw + 4 * TC * 64 + t * 64 + sub * 4);
;         const float v = bv[t * 16 + rowl];
;         const float sa = dpp_sum16((S0 * a4.x + S1 * a4.y) + (S2 * a4.z + S3 * a4.w));
;         S0 = (S0 * w4.x + v * k4.x) + sa * b4.x;
;         S1 = (S1 * w4.y + v * k4.y) + sa * b4.y;
;         S2 = (S2 * w4.z + v * k4.z) + sa * b4.z;
;         S3 = (S3 * w4.w + v * k4.w) + sa * b4.w;
;         yreg[t] = (S0 * r4.x + S1 * r4.y) + (S2 * r4.z + S3 * r4.w);
;       }
.Lrw_nosb_p0:
	s_add_u32 s4, s4, 0x18000
	s_addc_u32 s5, s5, 0
	s_add_u32 s6, s6, 0x8000
	s_addc_u32 s7, s7, 0
	s_add_u32 s8, s8, 0x8000
	s_addc_u32 s9, s9, 0
	s_add_u32 s16, s16, 0x400
	s_addc_u32 s17, s17, 0
	s_mov_b32 s0, 0
	s_mov_b32 s1, 0
	s_waitcnt lgkmcnt(0)
	s_barrier
	v_mov_b32_e32 v10, v47
	v_mov_b32_e32 v11, v136
	s_nop 0
	ds_read_b128 v[56:59], v10 offset:8192
	ds_read_b128 v[48:51], v10
	ds_read_b128 v[52:55], v10 offset:4096
	ds_read_b128 v[60:63], v10 offset:12288
	ds_read_b128 v[80:83], v10 offset:16384
	ds_read_b128 v[88:91], v11 offset:0
	ds_read_b128 v[92:95], v11 offset:16
	ds_read_b128 v[96:99], v11 offset:32
	ds_read_b128 v[100:103], v11 offset:48
.Lrw_chunk:
	s_cmp_eq_u32 s0, 512
	s_cbranch_scc1 .Lrw_noload
	global_load_dwordx2 v[34:35], v28, s[4:5]
	global_load_dwordx2 v[36:37], v28, s[4:5] offset:2048
	global_load_dwordx2 v[38:39], v29, s[6:7]
	global_load_dwordx2 v[40:41], v29, s[8:9]
	global_load_ushort v42, v30, s[4:5]
.Lrw_noload:
	ds_read_b128 v[72:75], v10 offset:8448
	ds_read_b128 v[64:67], v10 offset:256
	s_waitcnt lgkmcnt(2)
	v_pk_mul_f32 v[120:121], v[12:13], v[56:57]
	v_pk_fma_f32 v[120:121], v[14:15], v[58:59], v[120:121]
	v_pk_mul_f32 v[122:123], v[12:13], v[48:49]
	v_add_f32_e32 v128, v120, v121
	v_pk_mul_f32 v[124:125], v[14:15], v[50:51]
	v_pk_fma_f32 v[122:123], v[52:53], v[88:89], v[122:123] op_sel_hi:[1,0,1]
	v_add_f32_dpp v128, v128, v128 quad_perm:[1,0,3,2] row_mask:0xf bank_mask:0xf bound_ctrl:1
	v_pk_fma_f32 v[124:125], v[54:55], v[88:89], v[124:125] op_sel_hi:[1,0,1]
	ds_read_b128 v[68:71], v10 offset:4352
	v_add_f32_dpp v128, v128, v128 quad_perm:[2,3,0,1] row_mask:0xf bank_mask:0xf bound_ctrl:1
	ds_read_b128 v[76:79], v10 offset:12544
	ds_read_b128 v[84:87], v10 offset:16640
	v_add_f32_dpp v128, v128, v128 row_half_mirror row_mask:0xf bank_mask:0xf bound_ctrl:1
	s_nop 1
	v_add_f32_dpp v130, v128, v128 row_mirror row_mask:0xf bank_mask:0xf bound_ctrl:1
	v_pk_fma_f32 v[12:13], v[60:61], v[130:131], v[122:123] op_sel_hi:[1,0,1]
	v_pk_fma_f32 v[14:15], v[62:63], v[130:131], v[124:125] op_sel_hi:[1,0,1]
	v_pk_mul_f32 v[126:127], v[12:13], v[80:81]
	v_pk_fma_f32 v[126:127], v[14:15], v[82:83], v[126:127]
	ds_read_b128 v[56:59], v10 offset:8704
	ds_read_b128 v[48:51], v10 offset:512
	s_waitcnt lgkmcnt(2)
	v_pk_mul_f32 v[120:121], v[12:13], v[72:73]
	v_pk_fma_f32 v[120:121], v[14:15], v[74:75], v[120:121]
	v_pk_mul_f32 v[122:123], v[12:13], v[64:65]
	v_add_f32_e32 v128, v120, v121
	v_pk_mul_f32 v[124:125], v[14:15], v[66:67]
	v_pk_fma_f32 v[122:123], v[68:69], v[88:89], v[122:123] op_sel:[0,1,0] op_sel_hi:[1,1,1]
	v_add_f32_dpp v128, v128, v128 quad_perm:[1,0,3,2] row_mask:0xf bank_mask:0xf bound_ctrl:1
	v_pk_fma_f32 v[124:125], v[70:71], v[88:89], v[124:125] op_sel:[0,1,0] op_sel_hi:[1,1,1]
	ds_read_b128 v[52:55], v10 offset:4608
	v_add_f32_dpp v128, v128, v128 quad_perm:[2,3,0,1] row_mask:0xf bank_mask:0xf bound_ctrl:1
	ds_read_b128 v[60:63], v10 offset:12800
	ds_read_b128 v[80:83], v10 offset:16896
	v_add_f32_dpp v128, v128, v128 row_half_mirror row_mask:0xf bank_mask:0xf bound_ctrl:1
	v_add_f32_e32 v104, v126, v127
	s_nop 0
	v_add_f32_dpp v130, v128, v128 row_mirror row_mask:0xf bank_mask:0xf bound_ctrl:1
	v_pk_fma_f32 v[12:13], v[76:77], v[130:131], v[122:123] op_sel_hi:[1,0,1]
	v_pk_fma_f32 v[14:15], v[78:79], v[130:131], v[124:125] op_sel_hi:[1,0,1]
	v_pk_mul_f32 v[126:127], v[12:13], v[84:85]
	v_pk_fma_f32 v[126:127], v[14:15], v[86:87], v[126:127]
	ds_read_b128 v[72:75], v10 offset:8960
	ds_read_b128 v[64:67], v10 offset:768
	s_waitcnt lgkmcnt(2)
	v_pk_mul_f32 v[120:121], v[12:13], v[56:57]
	v_pk_fma_f32 v[120:121], v[14:15], v[58:59], v[120:121]
	v_pk_mul_f32 v[122:123], v[12:13], v[48:49]
	v_add_f32_e32 v128, v120, v121
	v_pk_mul_f32 v[124:125], v[14:15], v[50:51]
	v_pk_fma_f32 v[122:123], v[52:53], v[90:91], v[122:123] op_sel_hi:[1,0,1]
	v_add_f32_dpp v128, v128, v128 quad_perm:[1,0,3,2] row_mask:0xf bank_mask:0xf bound_ctrl:1
	v_pk_fma_f32 v[124:125], v[54:55], v[90:91], v[124:125] op_sel_hi:[1,0,1]
	ds_read_b128 v[68:71], v10 offset:4864
	v_add_f32_dpp v128, v128, v128 quad_perm:[2,3,0,1] row_mask:0xf bank_mask:0xf bound_ctrl:1
	ds_read_b128 v[76:79], v10 offset:13056
	ds_read_b128 v[84:87], v10 offset:17152
	v_add_f32_dpp v128, v128, v128 row_half_mirror row_mask:0xf bank_mask:0xf bound_ctrl:1
	v_add_f32_e32 v105, v126, v127
	s_nop 0
	v_add_f32_dpp v130, v128, v128 row_mirror row_mask:0xf bank_mask:0xf bound_ctrl:1
	v_pk_fma_f32 v[12:13], v[60:61], v[130:131], v[122:123] op_sel_hi:[1,0,1]
	v_pk_fma_f32 v[14:15], v[62:63], v[130:131], v[124:125] op_sel_hi:[1,0,1]
	v_pk_mul_f32 v[126:127], v[12:13], v[80:81]
	v_pk_fma_f32 v[126:127], v[14:15], v[82:83], v[126:127]
	ds_read_b128 v[56:59], v10 offset:9216
	ds_read_b128 v[48:51], v10 offset:1024
	s_waitcnt lgkmcnt(2)
	v_pk_mul_f32 v[120:121], v[12:13], v[72:73]
	v_pk_fma_f32 v[120:121], v[14:15], v[74:75], v[120:121]
	v_pk_mul_f32 v[122:123], v[12:13], v[64:65]
	v_add_f32_e32 v128, v120, v121
	v_pk_mul_f32 v[124:125], v[14:15], v[66:67]
	v_pk_fma_f32 v[122:123], v[68:69], v[90:91], v[122:123] op_sel:[0,1,0] op_sel_hi:[1,1,1]
	v_add_f32_dpp v128, v128, v128 quad_perm:[1,0,3,2] row_mask:0xf bank_mask:0xf bound_ctrl:1
	v_pk_fma_f32 v[124:125], v[70:71], v[90:91], v[124:125] op_sel:[0,1,0] op_sel_hi:[1,1,1]
	ds_read_b128 v[52:55], v10 offset:5120
	v_add_f32_dpp v128, v128, v128 quad_perm:[2,3,0,1] row_mask:0xf bank_mask:0xf bound_ctrl:1
	ds_read_b128 v[60:63], v10 offset:13312
	ds_read_b128 v[80:83], v10 offset:17408
	v_add_f32_dpp v128, v128, v128 row_half_mirror row_mask:0xf bank_mask:0xf bound_ctrl:1
	v_add_f32_e32 v106, v126, v127
	s_nop 0
	v_add_f32_dpp v130, v128, v128 row_mirror row_mask:0xf bank_mask:0xf bound_ctrl:1
	v_pk_fma_f32 v[12:13], v[76:77], v[130:131], v[122:123] op_sel_hi:[1,0,1]
	v_pk_fma_f32 v[14:15], v[78:79], v[130:131], v[124:125] op_sel_hi:[1,0,1]
	v_pk_mul_f32 v[126:127], v[12:13], v[84:85]
	v_pk_fma_f32 v[126:127], v[14:15], v[86:87], v[126:127]
	ds_read_b128 v[72:75], v10 offset:9472
	ds_read_b128 v[64:67], v10 offset:1280
	s_waitcnt lgkmcnt(2)
; __device__ __forceinline__ void rwkv_item(const Params& p, int item, float* sm) {
;     ...
; #pragma unroll
;       for (int t = 0; t < TC; t++) {
;         const float4 w4 = *(const float4*)(bw + 0 * TC * 64 + t * 64 + sub * 4);
;         const float4 k4 = *(const float4*)(bw + 1 * TC * 64 + t * 64 + sub * 4);
;         const float4 a4 = *(const float4*)(bw + 2 * TC * 64 + t * 64 + sub * 4);
;         const float4 b4 = *(const float4*)(bw + 3 * TC * 64 + t * 64 + sub * 4);
;         const float4 r4 = *(const float4*)(bw + 4 * TC * 64 + t * 64 + sub * 4);
;         const float v = bv[t * 16 + rowl];
;         const float sa = dpp_sum16((S0 * a4.x + S1 * a4.y) + (S2 * a4.z + S3 * a4.w));
;         S0 = (S0 * w4.x + v * k4.x) + sa * b4.x;
;         S1 = (S1 * w4.y + v * k4.y) + sa * b4.y;
;         S2 = (S2 * w4.z + v * k4.z) + sa * b4.z;
;         S3 = (S3 * w4.w + v * k4.w) + sa * b4.w;
;         yreg[t] = (S0 * r4.x + S1 * r4.y) + (S2 * r4.z + S3 * r4.w);
;       }
	v_pk_mul_f32 v[120:121], v[12:13], v[56:57]
	v_pk_fma_f32 v[120:121], v[14:15], v[58:59], v[120:121]
	v_pk_mul_f32 v[122:123], v[12:13], v[48:49]
	v_add_f32_e32 v128, v120, v121
	v_pk_mul_f32 v[124:125], v[14:15], v[50:51]
	v_pk_fma_f32 v[122:123], v[52:53], v[92:93], v[122:123] op_sel_hi:[1,0,1]
	v_add_f32_dpp v128, v128, v128 quad_perm:[1,0,3,2] row_mask:0xf bank_mask:0xf bound_ctrl:1
	v_pk_fma_f32 v[124:125], v[54:55], v[92:93], v[124:125] op_sel_hi:[1,0,1]
	ds_read_b128 v[68:71], v10 offset:5376
	v_add_f32_dpp v128, v128, v128 quad_perm:[2,3,0,1] row_mask:0xf bank_mask:0xf bound_ctrl:1
	ds_read_b128 v[76:79], v10 offset:13568
	ds_read_b128 v[84:87], v10 offset:17664
	v_add_f32_dpp v128, v128, v128 row_half_mirror row_mask:0xf bank_mask:0xf bound_ctrl:1
	v_add_f32_e32 v107, v126, v127
	s_nop 0
	v_add_f32_dpp v130, v128, v128 row_mirror row_mask:0xf bank_mask:0xf bound_ctrl:1
	v_pk_fma_f32 v[12:13], v[60:61], v[130:131], v[122:123] op_sel_hi:[1,0,1]
	v_pk_fma_f32 v[14:15], v[62:63], v[130:131], v[124:125] op_sel_hi:[1,0,1]
	v_pk_mul_f32 v[126:127], v[12:13], v[80:81]
	v_pk_fma_f32 v[126:127], v[14:15], v[82:83], v[126:127]
	ds_read_b128 v[56:59], v10 offset:9728
	ds_read_b128 v[48:51], v10 offset:1536
	s_waitcnt lgkmcnt(2)
	v_pk_mul_f32 v[120:121], v[12:13], v[72:73]
	v_pk_fma_f32 v[120:121], v[14:15], v[74:75], v[120:121]
	v_pk_mul_f32 v[122:123], v[12:13], v[64:65]
	v_add_f32_e32 v128, v120, v121
	v_pk_mul_f32 v[124:125], v[14:15], v[66:67]
	v_pk_fma_f32 v[122:123], v[68:69], v[92:93], v[122:123] op_sel:[0,1,0] op_sel_hi:[1,1,1]
	v_add_f32_dpp v128, v128, v128 quad_perm:[1,0,3,2] row_mask:0xf bank_mask:0xf bound_ctrl:1
	v_pk_fma_f32 v[124:125], v[70:71], v[92:93], v[124:125] op_sel:[0,1,0] op_sel_hi:[1,1,1]
	ds_read_b128 v[52:55], v10 offset:5632
	v_add_f32_dpp v128, v128, v128 quad_perm:[2,3,0,1] row_mask:0xf bank_mask:0xf bound_ctrl:1
	ds_read_b128 v[60:63], v10 offset:13824
	ds_read_b128 v[80:83], v10 offset:17920
	v_add_f32_dpp v128, v128, v128 row_half_mirror row_mask:0xf bank_mask:0xf bound_ctrl:1
	v_add_f32_e32 v108, v126, v127
	s_nop 0
	v_add_f32_dpp v130, v128, v128 row_mirror row_mask:0xf bank_mask:0xf bound_ctrl:1
	v_pk_fma_f32 v[12:13], v[76:77], v[130:131], v[122:123] op_sel_hi:[1,0,1]
	v_pk_fma_f32 v[14:15], v[78:79], v[130:131], v[124:125] op_sel_hi:[1,0,1]
	v_pk_mul_f32 v[126:127], v[12:13], v[84:85]
	v_pk_fma_f32 v[126:127], v[14:15], v[86:87], v[126:127]
	ds_read_b128 v[72:75], v10 offset:9984
	ds_read_b128 v[64:67], v10 offset:1792
	s_waitcnt lgkmcnt(2)
	v_pk_mul_f32 v[120:121], v[12:13], v[56:57]
	v_pk_fma_f32 v[120:121], v[14:15], v[58:59], v[120:121]
	v_pk_mul_f32 v[122:123], v[12:13], v[48:49]
	v_add_f32_e32 v128, v120, v121
	v_pk_mul_f32 v[124:125], v[14:15], v[50:51]
	v_pk_fma_f32 v[122:123], v[52:53], v[94:95], v[122:123] op_sel_hi:[1,0,1]
	v_add_f32_dpp v128, v128, v128 quad_perm:[1,0,3,2] row_mask:0xf bank_mask:0xf bound_ctrl:1
	v_pk_fma_f32 v[124:125], v[54:55], v[94:95], v[124:125] op_sel_hi:[1,0,1]
	ds_read_b128 v[68:71], v10 offset:5888
	v_add_f32_dpp v128, v128, v128 quad_perm:[2,3,0,1] row_mask:0xf bank_mask:0xf bound_ctrl:1
	ds_read_b128 v[76:79], v10 offset:14080
	ds_read_b128 v[84:87], v10 offset:18176
	v_add_f32_dpp v128, v128, v128 row_half_mirror row_mask:0xf bank_mask:0xf bound_ctrl:1
	v_add_f32_e32 v109, v126, v127
	s_nop 0
	v_add_f32_dpp v130, v128, v128 row_mirror row_mask:0xf bank_mask:0xf bound_ctrl:1
	v_pk_fma_f32 v[12:13], v[60:61], v[130:131], v[122:123] op_sel_hi:[1,0,1]
	v_pk_fma_f32 v[14:15], v[62:63], v[130:131], v[124:125] op_sel_hi:[1,0,1]
	v_pk_mul_f32 v[126:127], v[12:13], v[80:81]
	v_pk_fma_f32 v[126:127], v[14:15], v[82:83], v[126:127]
	ds_read_b128 v[56:59], v10 offset:10240
	ds_read_b128 v[48:51], v10 offset:2048
	s_waitcnt lgkmcnt(2)
	v_pk_mul_f32 v[120:121], v[12:13], v[72:73]
	v_pk_fma_f32 v[120:121], v[14:15], v[74:75], v[120:121]
	v_pk_mul_f32 v[122:123], v[12:13], v[64:65]
	v_add_f32_e32 v128, v120, v121
	v_pk_mul_f32 v[124:125], v[14:15], v[66:67]
	v_pk_fma_f32 v[122:123], v[68:69], v[94:95], v[122:123] op_sel:[0,1,0] op_sel_hi:[1,1,1]
	v_add_f32_dpp v128, v128, v128 quad_perm:[1,0,3,2] row_mask:0xf bank_mask:0xf bound_ctrl:1
	v_pk_fma_f32 v[124:125], v[70:71], v[94:95], v[124:125] op_sel:[0,1,0] op_sel_hi:[1,1,1]
	ds_read_b128 v[52:55], v10 offset:6144
	v_add_f32_dpp v128, v128, v128 quad_perm:[2,3,0,1] row_mask:0xf bank_mask:0xf bound_ctrl:1
	ds_read_b128 v[60:63], v10 offset:14336
	ds_read_b128 v[80:83], v10 offset:18432
	v_add_f32_dpp v128, v128, v128 row_half_mirror row_mask:0xf bank_mask:0xf bound_ctrl:1
	v_add_f32_e32 v110, v126, v127
	s_nop 0
	v_add_f32_dpp v130, v128, v128 row_mirror row_mask:0xf bank_mask:0xf bound_ctrl:1
	v_pk_fma_f32 v[12:13], v[76:77], v[130:131], v[122:123] op_sel_hi:[1,0,1]
	v_pk_fma_f32 v[14:15], v[78:79], v[130:131], v[124:125] op_sel_hi:[1,0,1]
	v_pk_mul_f32 v[126:127], v[12:13], v[84:85]
	v_pk_fma_f32 v[126:127], v[14:15], v[86:87], v[126:127]
	ds_read_b128 v[72:75], v10 offset:10496
	ds_read_b128 v[64:67], v10 offset:2304
	s_waitcnt lgkmcnt(2)
; __device__ __forceinline__ void rwkv_item(const Params& p, int item, float* sm) {
;     ...
; #pragma unroll
;       for (int t = 0; t < TC; t++) {
;         const float4 w4 = *(const float4*)(bw + 0 * TC * 64 + t * 64 + sub * 4);
;         const float4 k4 = *(const float4*)(bw + 1 * TC * 64 + t * 64 + sub * 4);
;         const float4 a4 = *(const float4*)(bw + 2 * TC * 64 + t * 64 + sub * 4);
;         const float4 b4 = *(const float4*)(bw + 3 * TC * 64 + t * 64 + sub * 4);
;         const float4 r4 = *(const float4*)(bw + 4 * TC * 64 + t * 64 + sub * 4);
;         const float v = bv[t * 16 + rowl];
;         const float sa = dpp_sum16((S0 * a4.x + S1 * a4.y) + (S2 * a4.z + S3 * a4.w));
;         S0 = (S0 * w4.x + v * k4.x) + sa * b4.x;
;         S1 = (S1 * w4.y + v * k4.y) + sa * b4.y;
;         S2 = (S2 * w4.z + v * k4.z) + sa * b4.z;
;         S3 = (S3 * w4.w + v * k4.w) + sa * b4.w;
;         yreg[t] = (S0 * r4.x + S1 * r4.y) + (S2 * r4.z + S3 * r4.w);
;       }
	v_pk_mul_f32 v[120:121], v[12:13], v[56:57]
	v_pk_fma_f32 v[120:121], v[14:15], v[58:59], v[120:121]
	v_pk_mul_f32 v[122:123], v[12:13], v[48:49]
	v_add_f32_e32 v128, v120, v121
	v_pk_mul_f32 v[124:125], v[14:15], v[50:51]
	v_pk_fma_f32 v[122:123], v[52:53], v[96:97], v[122:123] op_sel_hi:[1,0,1]
	v_add_f32_dpp v128, v128, v128 quad_perm:[1,0,3,2] row_mask:0xf bank_mask:0xf bound_ctrl:1
	v_pk_fma_f32 v[124:125], v[54:55], v[96:97], v[124:125] op_sel_hi:[1,0,1]
	ds_read_b128 v[68:71], v10 offset:6400
	v_add_f32_dpp v128, v128, v128 quad_perm:[2,3,0,1] row_mask:0xf bank_mask:0xf bound_ctrl:1
	ds_read_b128 v[76:79], v10 offset:14592
	ds_read_b128 v[84:87], v10 offset:18688
	v_add_f32_dpp v128, v128, v128 row_half_mirror row_mask:0xf bank_mask:0xf bound_ctrl:1
	v_add_f32_e32 v111, v126, v127
	s_nop 0
	v_add_f32_dpp v130, v128, v128 row_mirror row_mask:0xf bank_mask:0xf bound_ctrl:1
	v_pk_fma_f32 v[12:13], v[60:61], v[130:131], v[122:123] op_sel_hi:[1,0,1]
	v_pk_fma_f32 v[14:15], v[62:63], v[130:131], v[124:125] op_sel_hi:[1,0,1]
	v_pk_mul_f32 v[126:127], v[12:13], v[80:81]
	v_pk_fma_f32 v[126:127], v[14:15], v[82:83], v[126:127]
	ds_read_b128 v[56:59], v10 offset:10752
	ds_read_b128 v[48:51], v10 offset:2560
	s_waitcnt lgkmcnt(2)
	v_pk_mul_f32 v[120:121], v[12:13], v[72:73]
	v_pk_fma_f32 v[120:121], v[14:15], v[74:75], v[120:121]
	v_pk_mul_f32 v[122:123], v[12:13], v[64:65]
	v_add_f32_e32 v128, v120, v121
	v_pk_mul_f32 v[124:125], v[14:15], v[66:67]
	v_pk_fma_f32 v[122:123], v[68:69], v[96:97], v[122:123] op_sel:[0,1,0] op_sel_hi:[1,1,1]
	v_add_f32_dpp v128, v128, v128 quad_perm:[1,0,3,2] row_mask:0xf bank_mask:0xf bound_ctrl:1
	v_pk_fma_f32 v[124:125], v[70:71], v[96:97], v[124:125] op_sel:[0,1,0] op_sel_hi:[1,1,1]
	ds_read_b128 v[52:55], v10 offset:6656
	v_add_f32_dpp v128, v128, v128 quad_perm:[2,3,0,1] row_mask:0xf bank_mask:0xf bound_ctrl:1
	ds_read_b128 v[60:63], v10 offset:14848
	ds_read_b128 v[80:83], v10 offset:18944
	v_add_f32_dpp v128, v128, v128 row_half_mirror row_mask:0xf bank_mask:0xf bound_ctrl:1
	v_add_f32_e32 v112, v126, v127
	s_nop 0
	v_add_f32_dpp v130, v128, v128 row_mirror row_mask:0xf bank_mask:0xf bound_ctrl:1
	v_pk_fma_f32 v[12:13], v[76:77], v[130:131], v[122:123] op_sel_hi:[1,0,1]
	v_pk_fma_f32 v[14:15], v[78:79], v[130:131], v[124:125] op_sel_hi:[1,0,1]
	v_pk_mul_f32 v[126:127], v[12:13], v[84:85]
	v_pk_fma_f32 v[126:127], v[14:15], v[86:87], v[126:127]
	ds_read_b128 v[72:75], v10 offset:11008
	ds_read_b128 v[64:67], v10 offset:2816
	s_waitcnt lgkmcnt(2)
	v_pk_mul_f32 v[120:121], v[12:13], v[56:57]
	v_pk_fma_f32 v[120:121], v[14:15], v[58:59], v[120:121]
	v_pk_mul_f32 v[122:123], v[12:13], v[48:49]
	v_add_f32_e32 v128, v120, v121
	v_pk_mul_f32 v[124:125], v[14:15], v[50:51]
	v_pk_fma_f32 v[122:123], v[52:53], v[98:99], v[122:123] op_sel_hi:[1,0,1]
	v_add_f32_dpp v128, v128, v128 quad_perm:[1,0,3,2] row_mask:0xf bank_mask:0xf bound_ctrl:1
	v_pk_fma_f32 v[124:125], v[54:55], v[98:99], v[124:125] op_sel_hi:[1,0,1]
	ds_read_b128 v[68:71], v10 offset:6912
	v_add_f32_dpp v128, v128, v128 quad_perm:[2,3,0,1] row_mask:0xf bank_mask:0xf bound_ctrl:1
	ds_read_b128 v[76:79], v10 offset:15104
	ds_read_b128 v[84:87], v10 offset:19200
	v_add_f32_dpp v128, v128, v128 row_half_mirror row_mask:0xf bank_mask:0xf bound_ctrl:1
	v_add_f32_e32 v113, v126, v127
	s_nop 0
	v_add_f32_dpp v130, v128, v128 row_mirror row_mask:0xf bank_mask:0xf bound_ctrl:1
	v_pk_fma_f32 v[12:13], v[60:61], v[130:131], v[122:123] op_sel_hi:[1,0,1]
	v_pk_fma_f32 v[14:15], v[62:63], v[130:131], v[124:125] op_sel_hi:[1,0,1]
	v_pk_mul_f32 v[126:127], v[12:13], v[80:81]
	v_pk_fma_f32 v[126:127], v[14:15], v[82:83], v[126:127]
	ds_read_b128 v[56:59], v10 offset:11264
	ds_read_b128 v[48:51], v10 offset:3072
	s_waitcnt lgkmcnt(2)
	v_pk_mul_f32 v[120:121], v[12:13], v[72:73]
	v_pk_fma_f32 v[120:121], v[14:15], v[74:75], v[120:121]
	v_pk_mul_f32 v[122:123], v[12:13], v[64:65]
	v_add_f32_e32 v128, v120, v121
	v_pk_mul_f32 v[124:125], v[14:15], v[66:67]
	v_pk_fma_f32 v[122:123], v[68:69], v[98:99], v[122:123] op_sel:[0,1,0] op_sel_hi:[1,1,1]
	v_add_f32_dpp v128, v128, v128 quad_perm:[1,0,3,2] row_mask:0xf bank_mask:0xf bound_ctrl:1
	v_pk_fma_f32 v[124:125], v[70:71], v[98:99], v[124:125] op_sel:[0,1,0] op_sel_hi:[1,1,1]
	ds_read_b128 v[52:55], v10 offset:7168
	v_add_f32_dpp v128, v128, v128 quad_perm:[2,3,0,1] row_mask:0xf bank_mask:0xf bound_ctrl:1
	ds_read_b128 v[60:63], v10 offset:15360
	ds_read_b128 v[80:83], v10 offset:19456
	v_add_f32_dpp v128, v128, v128 row_half_mirror row_mask:0xf bank_mask:0xf bound_ctrl:1
	v_add_f32_e32 v114, v126, v127
	s_nop 0
	v_add_f32_dpp v130, v128, v128 row_mirror row_mask:0xf bank_mask:0xf bound_ctrl:1
	v_pk_fma_f32 v[12:13], v[76:77], v[130:131], v[122:123] op_sel_hi:[1,0,1]
	v_pk_fma_f32 v[14:15], v[78:79], v[130:131], v[124:125] op_sel_hi:[1,0,1]
	v_pk_mul_f32 v[126:127], v[12:13], v[84:85]
	v_pk_fma_f32 v[126:127], v[14:15], v[86:87], v[126:127]
	ds_read_b128 v[72:75], v10 offset:11520
	ds_read_b128 v[64:67], v10 offset:3328
	s_waitcnt lgkmcnt(2)
; __device__ __forceinline__ void rwkv_item(const Params& p, int item, float* sm) {
;     ...
; #pragma unroll
;       for (int t = 0; t < TC; t++) {
;         const float4 w4 = *(const float4*)(bw + 0 * TC * 64 + t * 64 + sub * 4);
;         const float4 k4 = *(const float4*)(bw + 1 * TC * 64 + t * 64 + sub * 4);
;         const float4 a4 = *(const float4*)(bw + 2 * TC * 64 + t * 64 + sub * 4);
;         const float4 b4 = *(const float4*)(bw + 3 * TC * 64 + t * 64 + sub * 4);
;         const float4 r4 = *(const float4*)(bw + 4 * TC * 64 + t * 64 + sub * 4);
;         const float v = bv[t * 16 + rowl];
;         const float sa = dpp_sum16((S0 * a4.x + S1 * a4.y) + (S2 * a4.z + S3 * a4.w));
;         S0 = (S0 * w4.x + v * k4.x) + sa * b4.x;
;         S1 = (S1 * w4.y + v * k4.y) + sa * b4.y;
;         S2 = (S2 * w4.z + v * k4.z) + sa * b4.z;
;         S3 = (S3 * w4.w + v * k4.w) + sa * b4.w;
;         yreg[t] = (S0 * r4.x + S1 * r4.y) + (S2 * r4.z + S3 * r4.w);
;       }
; #pragma unroll
;       for (int t = 0; t < TC; t++) yreg[t] = dpp_sum16(yreg[t]);
	v_pk_mul_f32 v[120:121], v[12:13], v[56:57]
	v_pk_fma_f32 v[120:121], v[14:15], v[58:59], v[120:121]
	v_pk_mul_f32 v[122:123], v[12:13], v[48:49]
	v_add_f32_e32 v128, v120, v121
	v_pk_mul_f32 v[124:125], v[14:15], v[50:51]
	v_pk_fma_f32 v[122:123], v[52:53], v[100:101], v[122:123] op_sel_hi:[1,0,1]
	v_add_f32_dpp v128, v128, v128 quad_perm:[1,0,3,2] row_mask:0xf bank_mask:0xf bound_ctrl:1
	v_pk_fma_f32 v[124:125], v[54:55], v[100:101], v[124:125] op_sel_hi:[1,0,1]
	ds_read_b128 v[68:71], v10 offset:7424
	v_add_f32_dpp v128, v128, v128 quad_perm:[2,3,0,1] row_mask:0xf bank_mask:0xf bound_ctrl:1
	ds_read_b128 v[76:79], v10 offset:15616
	ds_read_b128 v[84:87], v10 offset:19712
	v_add_f32_dpp v128, v128, v128 row_half_mirror row_mask:0xf bank_mask:0xf bound_ctrl:1
	v_add_f32_e32 v115, v126, v127
	s_nop 0
	v_add_f32_dpp v130, v128, v128 row_mirror row_mask:0xf bank_mask:0xf bound_ctrl:1
	v_pk_fma_f32 v[12:13], v[60:61], v[130:131], v[122:123] op_sel_hi:[1,0,1]
	v_pk_fma_f32 v[14:15], v[62:63], v[130:131], v[124:125] op_sel_hi:[1,0,1]
	v_pk_mul_f32 v[126:127], v[12:13], v[80:81]
	v_pk_fma_f32 v[126:127], v[14:15], v[82:83], v[126:127]
	ds_read_b128 v[56:59], v10 offset:11776
	ds_read_b128 v[48:51], v10 offset:3584
	s_waitcnt lgkmcnt(2)
	v_pk_mul_f32 v[120:121], v[12:13], v[72:73]
	v_pk_fma_f32 v[120:121], v[14:15], v[74:75], v[120:121]
	v_pk_mul_f32 v[122:123], v[12:13], v[64:65]
	v_add_f32_e32 v128, v120, v121
	v_pk_mul_f32 v[124:125], v[14:15], v[66:67]
	v_pk_fma_f32 v[122:123], v[68:69], v[100:101], v[122:123] op_sel:[0,1,0] op_sel_hi:[1,1,1]
	v_add_f32_dpp v128, v128, v128 quad_perm:[1,0,3,2] row_mask:0xf bank_mask:0xf bound_ctrl:1
	v_pk_fma_f32 v[124:125], v[70:71], v[100:101], v[124:125] op_sel:[0,1,0] op_sel_hi:[1,1,1]
	ds_read_b128 v[52:55], v10 offset:7680
	v_add_f32_dpp v128, v128, v128 quad_perm:[2,3,0,1] row_mask:0xf bank_mask:0xf bound_ctrl:1
	ds_read_b128 v[60:63], v10 offset:15872
	ds_read_b128 v[80:83], v10 offset:19968
	v_add_f32_dpp v128, v128, v128 row_half_mirror row_mask:0xf bank_mask:0xf bound_ctrl:1
	v_add_f32_e32 v116, v126, v127
	s_nop 0
	v_add_f32_dpp v130, v128, v128 row_mirror row_mask:0xf bank_mask:0xf bound_ctrl:1
	v_pk_fma_f32 v[12:13], v[76:77], v[130:131], v[122:123] op_sel_hi:[1,0,1]
	v_pk_fma_f32 v[14:15], v[78:79], v[130:131], v[124:125] op_sel_hi:[1,0,1]
	v_pk_mul_f32 v[126:127], v[12:13], v[84:85]
	v_pk_fma_f32 v[126:127], v[14:15], v[86:87], v[126:127]
	ds_read_b128 v[72:75], v10 offset:12032
	ds_read_b128 v[64:67], v10 offset:3840
	s_waitcnt lgkmcnt(2)
	v_pk_mul_f32 v[120:121], v[12:13], v[56:57]
	v_pk_fma_f32 v[120:121], v[14:15], v[58:59], v[120:121]
	v_pk_mul_f32 v[122:123], v[12:13], v[48:49]
	v_add_f32_e32 v128, v120, v121
	v_pk_mul_f32 v[124:125], v[14:15], v[50:51]
	v_pk_fma_f32 v[122:123], v[52:53], v[102:103], v[122:123] op_sel_hi:[1,0,1]
	v_add_f32_dpp v128, v128, v128 quad_perm:[1,0,3,2] row_mask:0xf bank_mask:0xf bound_ctrl:1
	v_pk_fma_f32 v[124:125], v[54:55], v[102:103], v[124:125] op_sel_hi:[1,0,1]
	ds_read_b128 v[68:71], v10 offset:7936
	v_add_f32_dpp v128, v128, v128 quad_perm:[2,3,0,1] row_mask:0xf bank_mask:0xf bound_ctrl:1
	ds_read_b128 v[76:79], v10 offset:16128
	ds_read_b128 v[84:87], v10 offset:20224
	v_add_f32_dpp v128, v128, v128 row_half_mirror row_mask:0xf bank_mask:0xf bound_ctrl:1
	v_add_f32_e32 v117, v126, v127
	s_nop 0
	v_add_f32_dpp v130, v128, v128 row_mirror row_mask:0xf bank_mask:0xf bound_ctrl:1
	v_pk_fma_f32 v[12:13], v[60:61], v[130:131], v[122:123] op_sel_hi:[1,0,1]
	v_pk_fma_f32 v[14:15], v[62:63], v[130:131], v[124:125] op_sel_hi:[1,0,1]
	v_pk_mul_f32 v[126:127], v[12:13], v[80:81]
	v_pk_fma_f32 v[126:127], v[14:15], v[82:83], v[126:127]
	s_waitcnt lgkmcnt(0)
	v_pk_mul_f32 v[120:121], v[12:13], v[72:73]
	v_pk_fma_f32 v[120:121], v[14:15], v[74:75], v[120:121]
	v_pk_mul_f32 v[122:123], v[12:13], v[64:65]
	v_add_f32_e32 v128, v120, v121
	v_pk_mul_f32 v[124:125], v[14:15], v[66:67]
	v_pk_fma_f32 v[122:123], v[68:69], v[102:103], v[122:123] op_sel:[0,1,0] op_sel_hi:[1,1,1]
	v_add_f32_dpp v128, v128, v128 quad_perm:[1,0,3,2] row_mask:0xf bank_mask:0xf bound_ctrl:1
	v_pk_fma_f32 v[124:125], v[70:71], v[102:103], v[124:125] op_sel:[0,1,0] op_sel_hi:[1,1,1]
	s_nop 0
	v_add_f32_dpp v128, v128, v128 quad_perm:[2,3,0,1] row_mask:0xf bank_mask:0xf bound_ctrl:1
	s_nop 1
	v_add_f32_dpp v128, v128, v128 row_half_mirror row_mask:0xf bank_mask:0xf bound_ctrl:1
	v_add_f32_e32 v118, v126, v127
	s_nop 0
	v_add_f32_dpp v130, v128, v128 row_mirror row_mask:0xf bank_mask:0xf bound_ctrl:1
	v_pk_fma_f32 v[12:13], v[76:77], v[130:131], v[122:123] op_sel_hi:[1,0,1]
	v_pk_fma_f32 v[14:15], v[78:79], v[130:131], v[124:125] op_sel_hi:[1,0,1]
	v_pk_mul_f32 v[126:127], v[12:13], v[84:85]
	v_pk_fma_f32 v[126:127], v[14:15], v[86:87], v[126:127]
	v_add_f32_e32 v119, v126, v127
	v_add_f32_dpp v104, v104, v104 quad_perm:[1,0,3,2] row_mask:0xf bank_mask:0xf bound_ctrl:1
	v_add_f32_dpp v105, v105, v105 quad_perm:[1,0,3,2] row_mask:0xf bank_mask:0xf bound_ctrl:1
	v_add_f32_dpp v106, v106, v106 quad_perm:[1,0,3,2] row_mask:0xf bank_mask:0xf bound_ctrl:1
	v_add_f32_dpp v107, v107, v107 quad_perm:[1,0,3,2] row_mask:0xf bank_mask:0xf bound_ctrl:1
	v_add_f32_dpp v108, v108, v108 quad_perm:[1,0,3,2] row_mask:0xf bank_mask:0xf bound_ctrl:1
	v_add_f32_dpp v109, v109, v109 quad_perm:[1,0,3,2] row_mask:0xf bank_mask:0xf bound_ctrl:1
	v_add_f32_dpp v110, v110, v110 quad_perm:[1,0,3,2] row_mask:0xf bank_mask:0xf bound_ctrl:1
	v_add_f32_dpp v111, v111, v111 quad_perm:[1,0,3,2] row_mask:0xf bank_mask:0xf bound_ctrl:1
	v_add_f32_dpp v112, v112, v112 quad_perm:[1,0,3,2] row_mask:0xf bank_mask:0xf bound_ctrl:1
; __device__ __forceinline__ void rwkv_item(const Params& p, int item, float* sm) {
;     ...
; #pragma unroll
;       for (int t = 0; t < TC; t++) yreg[t] = dpp_sum16(yreg[t]);
;       if (sub == 0) {
; #pragma unroll
;         for (int t = 0; t < TC; t++) by[t * 16 + rowl] = yreg[t];
;       }
;     }
;     if (c + 1 < NCH) RW_STORE(bi ^ 1, t0 + TC)
	v_add_f32_dpp v113, v113, v113 quad_perm:[1,0,3,2] row_mask:0xf bank_mask:0xf bound_ctrl:1
	v_add_f32_dpp v114, v114, v114 quad_perm:[1,0,3,2] row_mask:0xf bank_mask:0xf bound_ctrl:1
	v_add_f32_dpp v115, v115, v115 quad_perm:[1,0,3,2] row_mask:0xf bank_mask:0xf bound_ctrl:1
	v_add_f32_dpp v116, v116, v116 quad_perm:[1,0,3,2] row_mask:0xf bank_mask:0xf bound_ctrl:1
	v_add_f32_dpp v117, v117, v117 quad_perm:[1,0,3,2] row_mask:0xf bank_mask:0xf bound_ctrl:1
	v_add_f32_dpp v118, v118, v118 quad_perm:[1,0,3,2] row_mask:0xf bank_mask:0xf bound_ctrl:1
	v_add_f32_dpp v119, v119, v119 quad_perm:[1,0,3,2] row_mask:0xf bank_mask:0xf bound_ctrl:1
	v_add_f32_dpp v104, v104, v104 quad_perm:[2,3,0,1] row_mask:0xf bank_mask:0xf bound_ctrl:1
	v_add_f32_dpp v105, v105, v105 quad_perm:[2,3,0,1] row_mask:0xf bank_mask:0xf bound_ctrl:1
	v_add_f32_dpp v106, v106, v106 quad_perm:[2,3,0,1] row_mask:0xf bank_mask:0xf bound_ctrl:1
	v_add_f32_dpp v107, v107, v107 quad_perm:[2,3,0,1] row_mask:0xf bank_mask:0xf bound_ctrl:1
	v_add_f32_dpp v108, v108, v108 quad_perm:[2,3,0,1] row_mask:0xf bank_mask:0xf bound_ctrl:1
	v_add_f32_dpp v109, v109, v109 quad_perm:[2,3,0,1] row_mask:0xf bank_mask:0xf bound_ctrl:1
	v_add_f32_dpp v110, v110, v110 quad_perm:[2,3,0,1] row_mask:0xf bank_mask:0xf bound_ctrl:1
	v_add_f32_dpp v111, v111, v111 quad_perm:[2,3,0,1] row_mask:0xf bank_mask:0xf bound_ctrl:1
	v_add_f32_dpp v112, v112, v112 quad_perm:[2,3,0,1] row_mask:0xf bank_mask:0xf bound_ctrl:1
	v_add_f32_dpp v113, v113, v113 quad_perm:[2,3,0,1] row_mask:0xf bank_mask:0xf bound_ctrl:1
	v_add_f32_dpp v114, v114, v114 quad_perm:[2,3,0,1] row_mask:0xf bank_mask:0xf bound_ctrl:1
	v_add_f32_dpp v115, v115, v115 quad_perm:[2,3,0,1] row_mask:0xf bank_mask:0xf bound_ctrl:1
	v_add_f32_dpp v116, v116, v116 quad_perm:[2,3,0,1] row_mask:0xf bank_mask:0xf bound_ctrl:1
	v_add_f32_dpp v117, v117, v117 quad_perm:[2,3,0,1] row_mask:0xf bank_mask:0xf bound_ctrl:1
	v_add_f32_dpp v118, v118, v118 quad_perm:[2,3,0,1] row_mask:0xf bank_mask:0xf bound_ctrl:1
	v_add_f32_dpp v119, v119, v119 quad_perm:[2,3,0,1] row_mask:0xf bank_mask:0xf bound_ctrl:1
	v_add_f32_dpp v104, v104, v104 row_half_mirror row_mask:0xf bank_mask:0xf bound_ctrl:1
	v_add_f32_dpp v105, v105, v105 row_half_mirror row_mask:0xf bank_mask:0xf bound_ctrl:1
	v_add_f32_dpp v106, v106, v106 row_half_mirror row_mask:0xf bank_mask:0xf bound_ctrl:1
	v_add_f32_dpp v107, v107, v107 row_half_mirror row_mask:0xf bank_mask:0xf bound_ctrl:1
	v_add_f32_dpp v108, v108, v108 row_half_mirror row_mask:0xf bank_mask:0xf bound_ctrl:1
	v_add_f32_dpp v109, v109, v109 row_half_mirror row_mask:0xf bank_mask:0xf bound_ctrl:1
	v_add_f32_dpp v110, v110, v110 row_half_mirror row_mask:0xf bank_mask:0xf bound_ctrl:1
	v_add_f32_dpp v111, v111, v111 row_half_mirror row_mask:0xf bank_mask:0xf bound_ctrl:1
	v_add_f32_dpp v112, v112, v112 row_half_mirror row_mask:0xf bank_mask:0xf bound_ctrl:1
	v_add_f32_dpp v113, v113, v113 row_half_mirror row_mask:0xf bank_mask:0xf bound_ctrl:1
	v_add_f32_dpp v114, v114, v114 row_half_mirror row_mask:0xf bank_mask:0xf bound_ctrl:1
	v_add_f32_dpp v115, v115, v115 row_half_mirror row_mask:0xf bank_mask:0xf bound_ctrl:1
	v_add_f32_dpp v116, v116, v116 row_half_mirror row_mask:0xf bank_mask:0xf bound_ctrl:1
	v_add_f32_dpp v117, v117, v117 row_half_mirror row_mask:0xf bank_mask:0xf bound_ctrl:1
	v_add_f32_dpp v118, v118, v118 row_half_mirror row_mask:0xf bank_mask:0xf bound_ctrl:1
	v_add_f32_dpp v119, v119, v119 row_half_mirror row_mask:0xf bank_mask:0xf bound_ctrl:1
	v_add_f32_dpp v104, v104, v104 row_mirror row_mask:0xf bank_mask:0xf bound_ctrl:1
	v_add_f32_dpp v105, v105, v105 row_mirror row_mask:0xf bank_mask:0xf bound_ctrl:1
	v_add_f32_dpp v106, v106, v106 row_mirror row_mask:0xf bank_mask:0xf bound_ctrl:1
	v_add_f32_dpp v107, v107, v107 row_mirror row_mask:0xf bank_mask:0xf bound_ctrl:1
	v_add_f32_dpp v108, v108, v108 row_mirror row_mask:0xf bank_mask:0xf bound_ctrl:1
	v_add_f32_dpp v109, v109, v109 row_mirror row_mask:0xf bank_mask:0xf bound_ctrl:1
	v_add_f32_dpp v110, v110, v110 row_mirror row_mask:0xf bank_mask:0xf bound_ctrl:1
	v_add_f32_dpp v111, v111, v111 row_mirror row_mask:0xf bank_mask:0xf bound_ctrl:1
	v_add_f32_dpp v112, v112, v112 row_mirror row_mask:0xf bank_mask:0xf bound_ctrl:1
	v_add_f32_dpp v113, v113, v113 row_mirror row_mask:0xf bank_mask:0xf bound_ctrl:1
	v_add_f32_dpp v114, v114, v114 row_mirror row_mask:0xf bank_mask:0xf bound_ctrl:1
	v_add_f32_dpp v115, v115, v115 row_mirror row_mask:0xf bank_mask:0xf bound_ctrl:1
	v_add_f32_dpp v116, v116, v116 row_mirror row_mask:0xf bank_mask:0xf bound_ctrl:1
	v_add_f32_dpp v117, v117, v117 row_mirror row_mask:0xf bank_mask:0xf bound_ctrl:1
	v_add_f32_dpp v118, v118, v118 row_mirror row_mask:0xf bank_mask:0xf bound_ctrl:1
	v_add_f32_dpp v119, v119, v119 row_mirror row_mask:0xf bank_mask:0xf bound_ctrl:1
	v_add_u32_e32 v45, s1, v134
	s_xor_b32 s29, s1, 0x5800
	v_add_u32_e32 v43, s29, v132
	v_add_u32_e32 v44, s29, v133
	ds_write2_b32 v45, v104, v105 offset0:0 offset1:16
	ds_write2_b32 v45, v106, v107 offset0:32 offset1:48
	ds_write2_b32 v45, v108, v109 offset0:64 offset1:80
	ds_write2_b32 v45, v110, v111 offset0:96 offset1:112
	ds_write2_b32 v45, v112, v113 offset0:128 offset1:144
	ds_write2_b32 v45, v114, v115 offset0:160 offset1:176
	ds_write2_b32 v45, v116, v117 offset0:192 offset1:208
	ds_write2_b32 v45, v118, v119 offset0:224 offset1:240
	s_cmp_eq_u32 s0, 512
	s_cbranch_scc1 .Lrw_noprep
; __device__ __forceinline__ void rwkv_item(const Params& p, int item, float* sm) {
;     ...
;     if (c + 1 < NCH) RW_STORE(bi ^ 1, t0 + TC)
;     __syncthreads();
;     {
;       const float* bb = sm + bi * BUF;
;       const float yv = bb[5 * TC * 64 + TC * 16 + TC + ltt * 16 + lrr];
;       const float mu = dpp_sum16(yv) * (1.f / 16.f);
;       yr[(size_t)(t0 + ltt) * D + h * 64 + rg * 16 + lrr] = f2bf(yv - mu);
;       if (lrr == 0) MU[(rowb + t0 + ltt) * 64 + h * 4 + rg] = mu;
;     }
;   }
	s_waitcnt vmcnt(0)
	v_lshlrev_b32_e32 v48, 16, v34
	v_and_b32_e32 v49, 0xffff0000, v34
	v_lshlrev_b32_e32 v50, 16, v35
	v_and_b32_e32 v51, 0xffff0000, v35
	v_lshlrev_b32_e32 v52, 16, v36
	v_and_b32_e32 v53, 0xffff0000, v36
	v_lshlrev_b32_e32 v54, 16, v37
	v_and_b32_e32 v55, 0xffff0000, v37
	v_lshlrev_b32_e32 v56, 16, v38
	v_and_b32_e32 v57, 0xffff0000, v38
	v_lshlrev_b32_e32 v58, 16, v39
	v_and_b32_e32 v59, 0xffff0000, v39
	v_lshlrev_b32_e32 v60, 16, v40
	v_and_b32_e32 v61, 0xffff0000, v40
	v_lshlrev_b32_e32 v62, 16, v41
	v_and_b32_e32 v63, 0xffff0000, v41
	v_lshlrev_b32_e32 v64, 16, v42
	v_pk_mul_f32 v[68:69], v[52:53], v[16:17]
	v_pk_mul_f32 v[70:71], v[54:55], v[18:19]
	v_pk_mul_f32 v[72:73], v[68:69], v[68:69]
	v_pk_fma_f32 v[72:73], v[70:71], v[70:71], v[72:73]
	v_pk_add_f32 v[76:77], v[56:57], s[20:21]
	v_add_f32_e32 v74, v72, v73
	v_pk_add_f32 v[78:79], v[58:59], s[20:21]
	v_pk_mul_f32 v[84:85], v[60:61], s[22:23]
	v_add_f32_dpp v74, v74, v74 quad_perm:[1,0,3,2] row_mask:0xf bank_mask:0xf bound_ctrl:1
	v_pk_mul_f32 v[86:87], v[62:63], s[22:23]
	v_pk_fma_f32 v[76:77], v[76:77], v[20:21], s[30:31]
	v_add_f32_dpp v74, v74, v74 quad_perm:[2,3,0,1] row_mask:0xf bank_mask:0xf bound_ctrl:1
	v_pk_fma_f32 v[78:79], v[78:79], v[22:23], s[30:31]
	v_exp_f32_e32 v84, v84
	v_add_f32_dpp v74, v74, v74 row_half_mirror row_mask:0xf bank_mask:0xf bound_ctrl:1
	v_exp_f32_e32 v85, v85
	v_exp_f32_e32 v86, v86
	v_add_f32_dpp v74, v74, v74 row_mirror row_mask:0xf bank_mask:0xf bound_ctrl:1
	v_exp_f32_e32 v87, v87
	v_pk_mul_f32 v[80:81], v[52:53], v[76:77]
	v_add_f32_e32 v74, 0x358637bd, v74
	v_pk_mul_f32 v[82:83], v[54:55], v[78:79]
	v_rsq_f32_e32 v120, v74
	ds_write_b128 v43, v[84:87]
	ds_write_b128 v43, v[48:51] offset:16384
	ds_write_b32 v44, v64
	ds_write_b128 v43, v[80:83] offset:4096
	v_pk_mul_f32 v[124:125], v[68:69], v[120:121] op_sel_hi:[1,0] neg_lo:[0,1] neg_hi:[0,1]
	v_pk_mul_f32 v[126:127], v[70:71], v[120:121] op_sel_hi:[1,0] neg_lo:[0,1] neg_hi:[0,1]
	v_pk_mul_f32 v[100:101], v[124:125], v[56:57] neg_lo:[1,0] neg_hi:[1,0]
	v_pk_mul_f32 v[102:103], v[126:127], v[58:59] neg_lo:[1,0] neg_hi:[1,0]
	ds_write_b128 v43, v[124:127] offset:8192
	ds_write_b128 v43, v[100:103] offset:12288
	s_cmp_lg_u32 s18, 0
	s_cbranch_scc1 .Lrw_nosb_p1
	v_pk_mul_f32 v[104:105], v[48:49], v[80:81]
	v_pk_mul_f32 v[106:107], v[50:51], v[82:83]
	v_pk_mul_f32 v[108:109], v[104:105], v[24:25]
	v_pk_fma_f32 v[108:109], v[106:107], v[26:27], v[108:109]
	v_add_f32_e32 v110, v108, v109
	s_nop 1
	v_add_f32_dpp v110, v110, v110 quad_perm:[1,0,3,2] row_mask:0xf bank_mask:0xf bound_ctrl:1
	s_nop 1
	v_add_f32_dpp v110, v110, v110 quad_perm:[2,3,0,1] row_mask:0xf bank_mask:0xf bound_ctrl:1
	s_nop 1
	v_add_f32_dpp v110, v110, v110 row_half_mirror row_mask:0xf bank_mask:0xf bound_ctrl:1
	s_nop 1
	v_add_f32_dpp v110, v110, v110 row_mirror row_mask:0xf bank_mask:0xf bound_ctrl:1
	global_store_dword v33, v110, s[16:17]
.Lrw_nosb_p1:
	s_add_u32 s4, s4, 0x18000
	s_addc_u32 s5, s5, 0
	s_add_u32 s6, s6, 0x8000
	s_addc_u32 s7, s7, 0
	s_add_u32 s8, s8, 0x8000
	s_addc_u32 s9, s9, 0
	s_add_u32 s16, s16, 0x400
	s_addc_u32 s17, s17, 0
.Lrw_noprep:
	v_add_u32_e32 v46, s1, v135
	v_add_u32_e32 v10, s29, v47
	v_add_u32_e32 v11, s29, v136
	s_waitcnt lgkmcnt(0)
	s_barrier
	ds_read_b32 v120, v46
	ds_read_b128 v[56:59], v10 offset:8192
	ds_read_b128 v[48:51], v10
	ds_read_b128 v[52:55], v10 offset:4096
	ds_read_b128 v[60:63], v10 offset:12288
	ds_read_b128 v[80:83], v10 offset:16384
	ds_read_b128 v[88:91], v11 offset:0
	ds_read_b128 v[92:95], v11 offset:16
	ds_read_b128 v[96:99], v11 offset:32
	ds_read_b128 v[100:103], v11 offset:48
	s_waitcnt lgkmcnt(9)
	v_add_f32_dpp v122, v120, v120 quad_perm:[1,0,3,2] row_mask:0xf bank_mask:0xf bound_ctrl:1
	s_nop 1
	v_add_f32_dpp v122, v122, v122 quad_perm:[2,3,0,1] row_mask:0xf bank_mask:0xf bound_ctrl:1
	s_nop 1
	v_add_f32_dpp v122, v122, v122 row_half_mirror row_mask:0xf bank_mask:0xf bound_ctrl:1
	s_nop 1
	v_add_f32_dpp v122, v122, v122 row_mirror row_mask:0xf bank_mask:0xf bound_ctrl:1
	s_nop 0
	v_fmac_f32_e32 v120, 0xbd800000, v122
	v_mul_f32_e32 v122, 0x3d800000, v122
	v_cvt_pk_bf16_f32 v124, v120, v120
	global_store_dword v32, v122, s[14:15]
	global_store_short v31, v124, s[10:11]
	s_add_u32 s10, s10, 0x8000
	s_addc_u32 s11, s11, 0
	s_add_u32 s14, s14, 0x1000
	s_addc_u32 s15, s15, 0
	s_mov_b32 s1, s29
	s_add_i32 s0, s0, 1
	s_cmp_lg_u32 s0, 513
	s_cbranch_scc1 .Lrw_chunk
	s_waitcnt lgkmcnt(0)
	s_branch .LBB0_504
